# prologue converter v3: 2-deep load pipeline running flat across all segments (no drain at segment boundaries, round-robin over the concatenated item list)
# baseline (speedup 1.0000x reference)
; #define LAS __attribute__((address_space(3)))
; __device__ __forceinline__ void convert_segments(const Args& args, unsigned char* ws, LAS unsigned char* lds, int seg_lo, int seg_hi, int part_lo, int part_hi, int nparts, int wid, int nw, int wave, int lane) {
;     LAS float* scr = (LAS float*)(lds + wave * 16640);
; #pragma unroll 1
;     for (int sI = seg_lo; sI < seg_hi; ++sI) {
;         const Seg sg = seg_at(sI);
;         const int nblk = sg.ncols / 64, nit = (sg.K / 64) * nblk;
;         const float* W = args.in[sg.in_idx] + (size_t)sg.src_l * sg.K * sg.N;
;         bf16* WT = (bf16*)(ws + WS_W + (size_t)sg.layer * LAYER_W + (size_t)sg.wsub_mib * MiB);
;         const int it_lo = (int)((long)nit * part_lo / nparts), it_hi = (int)((long)nit * part_hi / nparts);
;         int it = it_lo + wid;
;         f32x4 v[16];
;         if (it < it_hi) { const int kb = it / nblk, nb = it - kb * nblk; tr_load(W + (size_t)(64 * kb) * sg.N + sg.scol + 64 * nb, sg.N, v, lane); }
; #pragma unroll 1
;         for (; it < it_hi; it += nw) {
;             const int kb = it / nblk, nb = it - kb * nblk;
;             const int drow = sg.ilv ? (256 * (nb >> 1) + 64 * (nb & 1) + sg.drow) : (sg.drow + 64 * nb);
;             tr_to_lds(v, scr, lane);
;             const int itn = it + nw;
;             if (itn < it_hi) { const int kbn = itn / nblk, nbn = itn - kbn * nblk; tr_load(W + (size_t)(64 * kbn) * sg.N + sg.scol + 64 * nbn, sg.N, v, lane); }
.LBB0_11:
	s_or_b64 exec, exec, s[4:5]
	s_load_dwordx2 s[36:37], s[0:1], 0xf0
	v_readlane_b32 s4, v254, 0
	s_lshr_b32 s89, s3, 6
	s_lshl_b32 s4, s4, 3
	s_lshl_b32 s38, s88, 3
	s_add_i32 s40, s4, s89
	s_waitcnt lgkmcnt(0)
	s_cmp_lt_i32 s36, 1
	s_cselect_b64 s[4:5], -1, 0
	s_cmp_gt_i32 s37, 0
	s_cselect_b64 s[6:7], -1, 0
	s_and_b64 s[4:5], s[4:5], s[6:7]
	s_andn2_b64 vcc, exec, s[4:5]
	s_cbranch_vccnz .LBB0_49
	s_mov_b32 s50, s40
	s_mov_b32 s63, s38
	s_cmpk_eq_i32 s88, 0x100
	s_cselect_b32 s61, 23, 26
	s_mov_b32 s70, -1
	s_mov_b32 s23, 0
	v_mbcnt_lo_u32_b32 v160, -1, 0
	v_mbcnt_hi_u32_b32 v160, -1, v160
	v_lshrrev_b32_e32 v161, 4, v160
	v_and_b32_e32 v162, 15, v160
	v_lshlrev_b32_e32 v162, 2, v162
	s_mul_i32 s66, s89, 0x4100
	v_mul_u32_u24_e32 v163, 0x41, v161
	v_add_u32_e32 v163, v163, v162
	v_lshl_add_u32 v163, v163, 2, s66
	v_and_b32_e32 v164, 7, v160
	v_lshrrev_b32_e32 v165, 3, v160
	v_mul_u32_u24_e32 v166, 0x208, v164
	v_add_u32_e32 v166, v166, v165
	v_lshl_add_u32 v166, v166, 2, s66
	v_add_u32_e32 v167, 0x410, v166
	s_load_dwordx2 s[68:69], s[0:1], 0xe8
	s_waitcnt lgkmcnt(0)
cvp_nx1:
	s_cmp_lt_u32 s50, s23
	s_cbranch_scc1 cvp_nf1
	s_sub_i32 s50, s50, s23
	s_mov_b32 s23, 0
	s_add_i32 s70, s70, 1
	s_cmp_ge_i32 s70, s61
	s_cbranch_scc1 cvp_done
	s_mul_i32 s4, s70, 40
	s_getpc_b64 s[6:7]
	s_add_u32 s6, s6, __const._Z6seg_ati.segs@rel32@lo+4
	s_addc_u32 s7, s7, __const._Z6seg_ati.segs@rel32@hi+12
	s_add_u32 s6, s6, s4
	s_addc_u32 s7, s7, 0
	s_load_dwordx8 s[8:15], s[6:7], 0x0
	s_load_dwordx2 s[18:19], s[6:7], 0x20
	s_waitcnt lgkmcnt(0)
	s_lshr_b32 s20, s13, 6
	s_lshr_b32 s21, s11, 6
	s_mul_i32 s22, s20, s21
	s_lshl_b32 s4, s8, 3
	s_load_dwordx2 s[24:25], s[0:1], s4
	s_mul_i32 s5, s11, s10
	s_mul_i32 s5, s5, s9
	s_lshl_b32 s5, s5, 2
	s_lshl_b32 s6, s12, 2
	s_add_u32 s5, s5, s6
	s_waitcnt lgkmcnt(0)
	s_add_u32 s24, s24, s5
	s_addc_u32 s25, s25, 0
	s_mul_i32 s5, s14, 0x1a400000
	s_lshl_b32 s6, s15, 20
	s_add_u32 s5, s5, s6
	s_add_u32 s5, s5, 0x2d400000
	s_add_u32 s26, s68, s5
	s_addc_u32 s27, s69, 0
	s_mov_b32 s41, 0
	s_mov_b32 s23, s22
	v_mul_lo_u32 v168, v161, s10
	v_add_u32_e32 v168, v168, v162
	v_lshlrev_b32_e32 v168, 2, v168
	s_lshl_b32 s48, s10, 4
	s_branch cvp_nx1
cvp_nf1:
	s_add_i32 s43, s41, s50
	s_add_i32 s50, s50, s63
	v_cvt_f32_u32_e32 v170, s43
	v_cvt_f32_u32_e32 v171, s20
	v_rcp_f32_e32 v171, v171
	s_nop 1
	v_mul_f32_e32 v170, v170, v171
	v_cvt_u32_f32_e32 v170, v170
	s_nop 1
	v_readfirstlane_b32 s46, v170
	s_mul_i32 s72, s46, s20
	s_sub_i32 s47, s43, s72
	s_cmp_lt_i32 s47, 0
	s_cselect_b32 s72, s20, 0
	s_cselect_b32 s73, 1, 0
	s_add_i32 s47, s47, s72
	s_sub_i32 s46, s46, s73
	s_cmp_ge_i32 s47, s20
	s_cselect_b32 s72, s20, 0
	s_cselect_b32 s73, 1, 0
	s_sub_i32 s47, s47, s72
	s_add_i32 s46, s46, s73
	s_cmp_ge_i32 s47, s20
	s_cselect_b32 s72, s20, 0
	s_cselect_b32 s73, 1, 0
	s_sub_i32 s47, s47, s72
	s_add_i32 s46, s46, s73
	s_mul_i32 s4, s46, s10
	s_add_i32 s4, s4, s47
	s_lshl_b32 s4, s4, 8
	s_add_u32 s56, s24, s4
	s_addc_u32 s57, s25, 0
	s_lshr_b32 s4, s47, 1
	s_lshl_b32 s4, s4, 8
	s_and_b32 s5, s47, 1
	s_lshl_b32 s5, s5, 6
	s_add_i32 s4, s4, s5
	s_lshl_b32 s5, s47, 6
	s_cmp_lg_u32 s19, 0
	s_cselect_b32 s4, s4, s5
	s_add_i32 s4, s4, s18
	s_mul_i32 s4, s4, s11
	s_lshl_b32 s5, s46, 6
	s_add_i32 s4, s4, s5
	s_lshl_b32 s4, s4, 1
	s_add_u32 s74, s26, s4
	s_addc_u32 s75, s27, 0
	s_mov_b32 s76, s11
	global_load_dwordx4 v[0:3], v168, s[56:57]
	s_add_u32 s56, s56, s48
	s_addc_u32 s57, s57, 0
	global_load_dwordx4 v[4:7], v168, s[56:57]
	s_add_u32 s56, s56, s48
	s_addc_u32 s57, s57, 0
	global_load_dwordx4 v[8:11], v168, s[56:57]
	s_add_u32 s56, s56, s48
	s_addc_u32 s57, s57, 0
	global_load_dwordx4 v[12:15], v168, s[56:57]
	s_add_u32 s56, s56, s48
	s_addc_u32 s57, s57, 0
	global_load_dwordx4 v[16:19], v168, s[56:57]
	s_add_u32 s56, s56, s48
	s_addc_u32 s57, s57, 0
	global_load_dwordx4 v[20:23], v168, s[56:57]
	s_add_u32 s56, s56, s48
	s_addc_u32 s57, s57, 0
	global_load_dwordx4 v[24:27], v168, s[56:57]
	s_add_u32 s56, s56, s48
	s_addc_u32 s57, s57, 0
	global_load_dwordx4 v[28:31], v168, s[56:57]
	s_add_u32 s56, s56, s48
	s_addc_u32 s57, s57, 0
	global_load_dwordx4 v[32:35], v168, s[56:57]
	s_add_u32 s56, s56, s48
	s_addc_u32 s57, s57, 0
	global_load_dwordx4 v[36:39], v168, s[56:57]
	s_add_u32 s56, s56, s48
	s_addc_u32 s57, s57, 0
	global_load_dwordx4 v[40:43], v168, s[56:57]
	s_add_u32 s56, s56, s48
	s_addc_u32 s57, s57, 0
	global_load_dwordx4 v[44:47], v168, s[56:57]
	s_add_u32 s56, s56, s48
	s_addc_u32 s57, s57, 0
	global_load_dwordx4 v[48:51], v168, s[56:57]
	s_add_u32 s56, s56, s48
	s_addc_u32 s57, s57, 0
	global_load_dwordx4 v[52:55], v168, s[56:57]
	s_add_u32 s56, s56, s48
	s_addc_u32 s57, s57, 0
	global_load_dwordx4 v[56:59], v168, s[56:57]
	s_add_u32 s56, s56, s48
	s_addc_u32 s57, s57, 0
	global_load_dwordx4 v[60:63], v168, s[56:57]
	s_mov_b32 s58, 1
	s_mov_b32 s59, 0
; #define LAS __attribute__((address_space(3)))
; __device__ __forceinline__ void convert_segments(const Args& args, unsigned char* ws, LAS unsigned char* lds, int seg_lo, int seg_hi, int part_lo, int part_hi, int nparts, int wid, int nw, int wave, int lane) {
;     LAS float* scr = (LAS float*)(lds + wave * 16640);
; #pragma unroll 1
;     for (int sI = seg_lo; sI < seg_hi; ++sI) {
;         const Seg sg = seg_at(sI);
;         const int nblk = sg.ncols / 64, nit = (sg.K / 64) * nblk;
;         const float* W = args.in[sg.in_idx] + (size_t)sg.src_l * sg.K * sg.N;
;         bf16* WT = (bf16*)(ws + WS_W + (size_t)sg.layer * LAYER_W + (size_t)sg.wsub_mib * MiB);
;         const int it_lo = (int)((long)nit * part_lo / nparts), it_hi = (int)((long)nit * part_hi / nparts);
;         int it = it_lo + wid;
;         f32x4 v[16];
;         if (it < it_hi) { const int kb = it / nblk, nb = it - kb * nblk; tr_load(W + (size_t)(64 * kb) * sg.N + sg.scol + 64 * nb, sg.N, v, lane); }
; #pragma unroll 1
;         for (; it < it_hi; it += nw) {
;             const int kb = it / nblk, nb = it - kb * nblk;
;             const int drow = sg.ilv ? (256 * (nb >> 1) + 64 * (nb & 1) + sg.drow) : (sg.drow + 64 * nb);
;             tr_to_lds(v, scr, lane);
;             const int itn = it + nw;
;             if (itn < it_hi) { const int kbn = itn / nblk, nbn = itn - kbn * nblk; tr_load(W + (size_t)(64 * kbn) * sg.N + sg.scol + 64 * nbn, sg.N, v, lane); }
cvp_nx2:
	s_cmp_lt_u32 s50, s23
	s_cbranch_scc1 cvp_nf2
	s_sub_i32 s50, s50, s23
	s_mov_b32 s23, 0
	s_add_i32 s70, s70, 1
	s_cmp_ge_i32 s70, s61
	s_cbranch_scc1 cvp_pre
	s_mul_i32 s4, s70, 40
	s_getpc_b64 s[6:7]
	s_add_u32 s6, s6, __const._Z6seg_ati.segs@rel32@lo+4
	s_addc_u32 s7, s7, __const._Z6seg_ati.segs@rel32@hi+12
	s_add_u32 s6, s6, s4
	s_addc_u32 s7, s7, 0
	s_load_dwordx8 s[8:15], s[6:7], 0x0
	s_load_dwordx2 s[18:19], s[6:7], 0x20
	s_waitcnt lgkmcnt(0)
	s_lshr_b32 s20, s13, 6
	s_lshr_b32 s21, s11, 6
	s_mul_i32 s22, s20, s21
	s_lshl_b32 s4, s8, 3
	s_load_dwordx2 s[24:25], s[0:1], s4
	s_mul_i32 s5, s11, s10
	s_mul_i32 s5, s5, s9
	s_lshl_b32 s5, s5, 2
	s_lshl_b32 s6, s12, 2
	s_add_u32 s5, s5, s6
	s_waitcnt lgkmcnt(0)
	s_add_u32 s24, s24, s5
	s_addc_u32 s25, s25, 0
	s_mul_i32 s5, s14, 0x1a400000
	s_lshl_b32 s6, s15, 20
	s_add_u32 s5, s5, s6
	s_add_u32 s5, s5, 0x2d400000
	s_add_u32 s26, s68, s5
	s_addc_u32 s27, s69, 0
	s_mov_b32 s41, 0
	s_mov_b32 s23, s22
	v_mul_lo_u32 v168, v161, s10
	v_add_u32_e32 v168, v168, v162
	v_lshlrev_b32_e32 v168, 2, v168
	s_lshl_b32 s48, s10, 4
	s_branch cvp_nx2
cvp_nf2:
	s_add_i32 s43, s41, s50
	s_add_i32 s50, s50, s63
	v_cvt_f32_u32_e32 v170, s43
	v_cvt_f32_u32_e32 v171, s20
	v_rcp_f32_e32 v171, v171
	s_nop 1
	v_mul_f32_e32 v170, v170, v171
	v_cvt_u32_f32_e32 v170, v170
	s_nop 1
	v_readfirstlane_b32 s46, v170
	s_mul_i32 s72, s46, s20
	s_sub_i32 s47, s43, s72
	s_cmp_lt_i32 s47, 0
	s_cselect_b32 s72, s20, 0
	s_cselect_b32 s73, 1, 0
	s_add_i32 s47, s47, s72
	s_sub_i32 s46, s46, s73
	s_cmp_ge_i32 s47, s20
	s_cselect_b32 s72, s20, 0
	s_cselect_b32 s73, 1, 0
	s_sub_i32 s47, s47, s72
	s_add_i32 s46, s46, s73
	s_cmp_ge_i32 s47, s20
	s_cselect_b32 s72, s20, 0
	s_cselect_b32 s73, 1, 0
	s_sub_i32 s47, s47, s72
	s_add_i32 s46, s46, s73
	s_mul_i32 s4, s46, s10
	s_add_i32 s4, s4, s47
	s_lshl_b32 s4, s4, 8
	s_add_u32 s56, s24, s4
	s_addc_u32 s57, s25, 0
	s_lshr_b32 s4, s47, 1
	s_lshl_b32 s4, s4, 8
	s_and_b32 s5, s47, 1
	s_lshl_b32 s5, s5, 6
	s_add_i32 s4, s4, s5
	s_lshl_b32 s5, s47, 6
	s_cmp_lg_u32 s19, 0
	s_cselect_b32 s4, s4, s5
	s_add_i32 s4, s4, s18
	s_mul_i32 s4, s4, s11
	s_lshl_b32 s5, s46, 6
	s_add_i32 s4, s4, s5
	s_lshl_b32 s4, s4, 1
	s_add_u32 s78, s26, s4
	s_addc_u32 s79, s27, 0
	s_mov_b32 s77, s11
	global_load_dwordx4 v[64:67], v168, s[56:57]
	s_add_u32 s56, s56, s48
	s_addc_u32 s57, s57, 0
	global_load_dwordx4 v[68:71], v168, s[56:57]
	s_add_u32 s56, s56, s48
	s_addc_u32 s57, s57, 0
	global_load_dwordx4 v[72:75], v168, s[56:57]
	s_add_u32 s56, s56, s48
	s_addc_u32 s57, s57, 0
	global_load_dwordx4 v[76:79], v168, s[56:57]
	s_add_u32 s56, s56, s48
	s_addc_u32 s57, s57, 0
	global_load_dwordx4 v[80:83], v168, s[56:57]
	s_add_u32 s56, s56, s48
	s_addc_u32 s57, s57, 0
	global_load_dwordx4 v[84:87], v168, s[56:57]
	s_add_u32 s56, s56, s48
	s_addc_u32 s57, s57, 0
	global_load_dwordx4 v[88:91], v168, s[56:57]
	s_add_u32 s56, s56, s48
	s_addc_u32 s57, s57, 0
	global_load_dwordx4 v[92:95], v168, s[56:57]
	s_add_u32 s56, s56, s48
	s_addc_u32 s57, s57, 0
	global_load_dwordx4 v[96:99], v168, s[56:57]
	s_add_u32 s56, s56, s48
	s_addc_u32 s57, s57, 0
	global_load_dwordx4 v[100:103], v168, s[56:57]
	s_add_u32 s56, s56, s48
	s_addc_u32 s57, s57, 0
	global_load_dwordx4 v[104:107], v168, s[56:57]
	s_add_u32 s56, s56, s48
	s_addc_u32 s57, s57, 0
	global_load_dwordx4 v[108:111], v168, s[56:57]
	s_add_u32 s56, s56, s48
	s_addc_u32 s57, s57, 0
	global_load_dwordx4 v[112:115], v168, s[56:57]
	s_add_u32 s56, s56, s48
	s_addc_u32 s57, s57, 0
	global_load_dwordx4 v[116:119], v168, s[56:57]
	s_add_u32 s56, s56, s48
	s_addc_u32 s57, s57, 0
	global_load_dwordx4 v[120:123], v168, s[56:57]
	s_add_u32 s56, s56, s48
	s_addc_u32 s57, s57, 0
	global_load_dwordx4 v[124:127], v168, s[56:57]
	s_mov_b32 s59, 1

; __device__ __forceinline__ void convert_segments(const Args& args, unsigned char* ws, LAS unsigned char* lds, int seg_lo, int seg_hi, int part_lo, int part_hi, int nparts, int wid, int nw, int wave, int lane) {
;     ...
;         for (; it < it_hi; it += nw) {
;             const int kb = it / nblk, nb = it - kb * nblk;
;             const int drow = sg.ilv ? (256 * (nb >> 1) + 64 * (nb & 1) + sg.drow) : (sg.drow + 64 * nb);
;             tr_to_lds(v, scr, lane);
;             const int itn = it + nw;
;             if (itn < it_hi) { const int kbn = itn / nblk, nbn = itn - kbn * nblk; tr_load(W + (size_t)(64 * kbn) * sg.N + sg.scol + 64 * nbn, sg.N, v, lane); }
cvp_stepA:
	s_cmp_lg_u32 s59, 0
	s_cbranch_scc0 cvp_w0A
	s_waitcnt vmcnt(32)
	s_branch cvp_goA

; #define LAS __attribute__((address_space(3)))
; #define LDS_WAIT() asm volatile("s_waitcnt lgkmcnt(0)" ::: "memory")
; __device__ __forceinline__ void tr_to_lds(const f32x4 (&v)[16], LAS float* scr, int lane) {
;     const int r4 = lane >> 4, c4 = (lane & 15) * 4;
; #pragma unroll
;     for (int i = 0; i < 16; ++i) { LAS float* s = scr + (4 * i + r4) * 65 + c4; s[0] = v[i].x; s[1] = v[i].y; s[2] = v[i].z; s[3] = v[i].w; }
;     LDS_WAIT(); asm volatile("" ::: "memory");
; }
; __device__ __forceinline__ void convert_segments(const Args& args, unsigned char* ws, LAS unsigned char* lds, int seg_lo, int seg_hi, int part_lo, int part_hi, int nparts, int wid, int nw, int wave, int lane) {
;     ...
;     for (int sI = seg_lo; sI < seg_hi; ++sI) {
;         const Seg sg = seg_at(sI);
;         const int nblk = sg.ncols / 64, nit = (sg.K / 64) * nblk;
;         const float* W = args.in[sg.in_idx] + (size_t)sg.src_l * sg.K * sg.N;
;         bf16* WT = (bf16*)(ws + WS_W + (size_t)sg.layer * LAYER_W + (size_t)sg.wsub_mib * MiB);
;         const int it_lo = (int)((long)nit * part_lo / nparts), it_hi = (int)((long)nit * part_hi / nparts);
;         int it = it_lo + wid;
;         f32x4 v[16];
;         if (it < it_hi) { const int kb = it / nblk, nb = it - kb * nblk; tr_load(W + (size_t)(64 * kb) * sg.N + sg.scol + 64 * nb, sg.N, v, lane); }
; #pragma unroll 1
;         for (; it < it_hi; it += nw) {
;             const int kb = it / nblk, nb = it - kb * nblk;
;             const int drow = sg.ilv ? (256 * (nb >> 1) + 64 * (nb & 1) + sg.drow) : (sg.drow + 64 * nb);
;             tr_to_lds(v, scr, lane);
;             const int itn = it + nw;
;             if (itn < it_hi) { const int kbn = itn / nblk, nbn = itn - kbn * nblk; tr_load(W + (size_t)(64 * kbn) * sg.N + sg.scol + 64 * nbn, sg.N, v, lane); }
cvp_goA:
	ds_write_b32 v163, v0 offset:0
	ds_write_b32 v163, v1 offset:4
	ds_write_b32 v163, v2 offset:8
	ds_write_b32 v163, v3 offset:12
	ds_write_b32 v163, v4 offset:1040
	ds_write_b32 v163, v5 offset:1044
	ds_write_b32 v163, v6 offset:1048
	ds_write_b32 v163, v7 offset:1052
	ds_write_b32 v163, v8 offset:2080
	ds_write_b32 v163, v9 offset:2084
	ds_write_b32 v163, v10 offset:2088
	ds_write_b32 v163, v11 offset:2092
	ds_write_b32 v163, v12 offset:3120
	ds_write_b32 v163, v13 offset:3124
	ds_write_b32 v163, v14 offset:3128
	ds_write_b32 v163, v15 offset:3132
	ds_write_b32 v163, v16 offset:4160
	ds_write_b32 v163, v17 offset:4164
	ds_write_b32 v163, v18 offset:4168
	ds_write_b32 v163, v19 offset:4172
	ds_write_b32 v163, v20 offset:5200
	ds_write_b32 v163, v21 offset:5204
	ds_write_b32 v163, v22 offset:5208
	ds_write_b32 v163, v23 offset:5212
	ds_write_b32 v163, v24 offset:6240
	ds_write_b32 v163, v25 offset:6244
	ds_write_b32 v163, v26 offset:6248
	ds_write_b32 v163, v27 offset:6252
	ds_write_b32 v163, v28 offset:7280
	ds_write_b32 v163, v29 offset:7284
	ds_write_b32 v163, v30 offset:7288
	ds_write_b32 v163, v31 offset:7292
	ds_write_b32 v163, v32 offset:8320
	ds_write_b32 v163, v33 offset:8324
	ds_write_b32 v163, v34 offset:8328
	ds_write_b32 v163, v35 offset:8332
	ds_write_b32 v163, v36 offset:9360
	ds_write_b32 v163, v37 offset:9364
	ds_write_b32 v163, v38 offset:9368
	ds_write_b32 v163, v39 offset:9372
	ds_write_b32 v163, v40 offset:10400
	ds_write_b32 v163, v41 offset:10404
	ds_write_b32 v163, v42 offset:10408
	ds_write_b32 v163, v43 offset:10412
	ds_write_b32 v163, v44 offset:11440
	ds_write_b32 v163, v45 offset:11444
	ds_write_b32 v163, v46 offset:11448
	ds_write_b32 v163, v47 offset:11452
	ds_write_b32 v163, v48 offset:12480
	ds_write_b32 v163, v49 offset:12484
	ds_write_b32 v163, v50 offset:12488
	ds_write_b32 v163, v51 offset:12492
	ds_write_b32 v163, v52 offset:13520
	ds_write_b32 v163, v53 offset:13524
	ds_write_b32 v163, v54 offset:13528
	ds_write_b32 v163, v55 offset:13532
	ds_write_b32 v163, v56 offset:14560
	ds_write_b32 v163, v57 offset:14564
	ds_write_b32 v163, v58 offset:14568
	ds_write_b32 v163, v59 offset:14572
	ds_write_b32 v163, v60 offset:15600
	ds_write_b32 v163, v61 offset:15604
	ds_write_b32 v163, v62 offset:15608
	ds_write_b32 v163, v63 offset:15612
	s_waitcnt lgkmcnt(0)
	s_mov_b32 s54, s74
	s_mov_b32 s55, s75
	s_lshl_b32 s49, s76, 4
	v_mul_lo_u32 v169, v165, s76
	v_lshl_add_u32 v169, v164, 3, v169
	v_lshlrev_b32_e32 v169, 1, v169
	s_mov_b32 s58, 0
cvp_nx3:
	s_cmp_lt_u32 s50, s23
	s_cbranch_scc1 cvp_nf3
	s_sub_i32 s50, s50, s23
	s_mov_b32 s23, 0
	s_add_i32 s70, s70, 1
	s_cmp_ge_i32 s70, s61
	s_cbranch_scc1 cvp_nlA
	s_mul_i32 s4, s70, 40
	s_getpc_b64 s[6:7]
	s_add_u32 s6, s6, __const._Z6seg_ati.segs@rel32@lo+4
	s_addc_u32 s7, s7, __const._Z6seg_ati.segs@rel32@hi+12
	s_add_u32 s6, s6, s4
	s_addc_u32 s7, s7, 0
	s_load_dwordx8 s[8:15], s[6:7], 0x0
	s_load_dwordx2 s[18:19], s[6:7], 0x20
	s_waitcnt lgkmcnt(0)
	s_lshr_b32 s20, s13, 6
	s_lshr_b32 s21, s11, 6
	s_mul_i32 s22, s20, s21
	s_lshl_b32 s4, s8, 3
	s_load_dwordx2 s[24:25], s[0:1], s4
	s_mul_i32 s5, s11, s10
	s_mul_i32 s5, s5, s9
	s_lshl_b32 s5, s5, 2
	s_lshl_b32 s6, s12, 2
	s_add_u32 s5, s5, s6
	s_waitcnt lgkmcnt(0)
	s_add_u32 s24, s24, s5
	s_addc_u32 s25, s25, 0
	s_mul_i32 s5, s14, 0x1a400000
	s_lshl_b32 s6, s15, 20
	s_add_u32 s5, s5, s6
	s_add_u32 s5, s5, 0x2d400000
	s_add_u32 s26, s68, s5
	s_addc_u32 s27, s69, 0
	s_mov_b32 s41, 0
	s_mov_b32 s23, s22
	v_mul_lo_u32 v168, v161, s10
	v_add_u32_e32 v168, v168, v162
	v_lshlrev_b32_e32 v168, 2, v168
	s_lshl_b32 s48, s10, 4
	s_branch cvp_nx3
cvp_nf3:
	s_add_i32 s43, s41, s50
	s_add_i32 s50, s50, s63
	v_cvt_f32_u32_e32 v170, s43
	v_cvt_f32_u32_e32 v171, s20
	v_rcp_f32_e32 v171, v171
	s_nop 1
	v_mul_f32_e32 v170, v170, v171
	v_cvt_u32_f32_e32 v170, v170
	s_nop 1
	v_readfirstlane_b32 s46, v170
	s_mul_i32 s72, s46, s20
	s_sub_i32 s47, s43, s72
	s_cmp_lt_i32 s47, 0
	s_cselect_b32 s72, s20, 0
	s_cselect_b32 s73, 1, 0
	s_add_i32 s47, s47, s72
	s_sub_i32 s46, s46, s73
	s_cmp_ge_i32 s47, s20
	s_cselect_b32 s72, s20, 0
	s_cselect_b32 s73, 1, 0
	s_sub_i32 s47, s47, s72
	s_add_i32 s46, s46, s73
	s_cmp_ge_i32 s47, s20
	s_cselect_b32 s72, s20, 0
	s_cselect_b32 s73, 1, 0
	s_sub_i32 s47, s47, s72
	s_add_i32 s46, s46, s73
	s_mul_i32 s4, s46, s10
	s_add_i32 s4, s4, s47
	s_lshl_b32 s4, s4, 8
	s_add_u32 s56, s24, s4
	s_addc_u32 s57, s25, 0
	s_lshr_b32 s4, s47, 1
	s_lshl_b32 s4, s4, 8
	s_and_b32 s5, s47, 1
	s_lshl_b32 s5, s5, 6
	s_add_i32 s4, s4, s5
	s_lshl_b32 s5, s47, 6
	s_cmp_lg_u32 s19, 0
	s_cselect_b32 s4, s4, s5
	s_add_i32 s4, s4, s18
	s_mul_i32 s4, s4, s11
	s_lshl_b32 s5, s46, 6
	s_add_i32 s4, s4, s5
	s_lshl_b32 s4, s4, 1
	s_add_u32 s74, s26, s4
	s_addc_u32 s75, s27, 0
	s_mov_b32 s76, s11
	global_load_dwordx4 v[0:3], v168, s[56:57]
	s_add_u32 s56, s56, s48
	s_addc_u32 s57, s57, 0
	global_load_dwordx4 v[4:7], v168, s[56:57]
	s_add_u32 s56, s56, s48
	s_addc_u32 s57, s57, 0
	global_load_dwordx4 v[8:11], v168, s[56:57]
	s_add_u32 s56, s56, s48
	s_addc_u32 s57, s57, 0
	global_load_dwordx4 v[12:15], v168, s[56:57]
	s_add_u32 s56, s56, s48
	s_addc_u32 s57, s57, 0
	global_load_dwordx4 v[16:19], v168, s[56:57]
	s_add_u32 s56, s56, s48
	s_addc_u32 s57, s57, 0
	global_load_dwordx4 v[20:23], v168, s[56:57]
	s_add_u32 s56, s56, s48
	s_addc_u32 s57, s57, 0
	global_load_dwordx4 v[24:27], v168, s[56:57]
	s_add_u32 s56, s56, s48
	s_addc_u32 s57, s57, 0
	global_load_dwordx4 v[28:31], v168, s[56:57]
	s_add_u32 s56, s56, s48
	s_addc_u32 s57, s57, 0
	global_load_dwordx4 v[32:35], v168, s[56:57]
	s_add_u32 s56, s56, s48
	s_addc_u32 s57, s57, 0
	global_load_dwordx4 v[36:39], v168, s[56:57]
	s_add_u32 s56, s56, s48
	s_addc_u32 s57, s57, 0
	global_load_dwordx4 v[40:43], v168, s[56:57]
	s_add_u32 s56, s56, s48
	s_addc_u32 s57, s57, 0
	global_load_dwordx4 v[44:47], v168, s[56:57]
	s_add_u32 s56, s56, s48
	s_addc_u32 s57, s57, 0
	global_load_dwordx4 v[48:51], v168, s[56:57]
	s_add_u32 s56, s56, s48
	s_addc_u32 s57, s57, 0
	global_load_dwordx4 v[52:55], v168, s[56:57]
	s_add_u32 s56, s56, s48
	s_addc_u32 s57, s57, 0
	global_load_dwordx4 v[56:59], v168, s[56:57]
	s_add_u32 s56, s56, s48
	s_addc_u32 s57, s57, 0
	global_load_dwordx4 v[60:63], v168, s[56:57]
	s_mov_b32 s58, 1
; #define LAS __attribute__((address_space(3)))
; #define LDS_WAIT() asm volatile("s_waitcnt lgkmcnt(0)" ::: "memory")
; __device__ __forceinline__ unsigned pk2(float lo, float hi) { const f32x2c v = {lo, hi}; return __builtin_bit_cast(unsigned, __builtin_convertvector(v, bf16x2c)); }
; __device__ __forceinline__ void tr_store(bf16* dst, int K, const LAS float* scr, int lane) {
;     const int c = lane & 7;
; #pragma unroll
;     for (int j = 0; j < 8; ++j) { const int n = (lane >> 3) + 8 * j; const LAS float* s = scr + (8 * c) * 65 + n;
;         v4u o; o.x = pk2(s[0], s[65]); o.y = pk2(s[130], s[195]); o.z = pk2(s[260], s[325]); o.w = pk2(s[390], s[455]);
;         *(v4u*)(dst + (size_t)n * K + 8 * c) = o; }
;     LDS_WAIT(); asm volatile("" ::: "memory");
; }
cvp_nlA:
	ds_read2_b32 v[128:129], v166 offset0:0 offset1:65
	ds_read2_b32 v[130:131], v166 offset0:130 offset1:195
	ds_read2_b32 v[132:133], v167 offset0:0 offset1:65
	ds_read2_b32 v[134:135], v167 offset0:130 offset1:195
	ds_read2_b32 v[136:137], v166 offset0:8 offset1:73
	ds_read2_b32 v[138:139], v166 offset0:138 offset1:203
	ds_read2_b32 v[140:141], v167 offset0:8 offset1:73
	ds_read2_b32 v[142:143], v167 offset0:138 offset1:203
	s_waitcnt lgkmcnt(4)
	v_cvt_pk_bf16_f32 v152, v128, v129
	v_cvt_pk_bf16_f32 v153, v130, v131
	v_cvt_pk_bf16_f32 v154, v132, v133
	v_cvt_pk_bf16_f32 v155, v134, v135
	global_store_dwordx4 v169, v[152:155], s[54:55]
	s_add_u32 s54, s54, s49
	s_addc_u32 s55, s55, 0
	ds_read2_b32 v[144:145], v166 offset0:16 offset1:81
	ds_read2_b32 v[146:147], v166 offset0:146 offset1:211
	ds_read2_b32 v[148:149], v167 offset0:16 offset1:81
	ds_read2_b32 v[150:151], v167 offset0:146 offset1:211
	s_waitcnt lgkmcnt(4)
	v_cvt_pk_bf16_f32 v156, v136, v137
	v_cvt_pk_bf16_f32 v157, v138, v139
	v_cvt_pk_bf16_f32 v158, v140, v141
	v_cvt_pk_bf16_f32 v159, v142, v143
	global_store_dwordx4 v169, v[156:159], s[54:55]
	s_add_u32 s54, s54, s49
	s_addc_u32 s55, s55, 0
	ds_read2_b32 v[128:129], v166 offset0:24 offset1:89
	ds_read2_b32 v[130:131], v166 offset0:154 offset1:219
	ds_read2_b32 v[132:133], v167 offset0:24 offset1:89
	ds_read2_b32 v[134:135], v167 offset0:154 offset1:219
	s_waitcnt lgkmcnt(4)
	v_cvt_pk_bf16_f32 v152, v144, v145
	v_cvt_pk_bf16_f32 v153, v146, v147
	v_cvt_pk_bf16_f32 v154, v148, v149
	v_cvt_pk_bf16_f32 v155, v150, v151
	global_store_dwordx4 v169, v[152:155], s[54:55]
	s_add_u32 s54, s54, s49
	s_addc_u32 s55, s55, 0
	ds_read2_b32 v[136:137], v166 offset0:32 offset1:97
	ds_read2_b32 v[138:139], v166 offset0:162 offset1:227
	ds_read2_b32 v[140:141], v167 offset0:32 offset1:97
	ds_read2_b32 v[142:143], v167 offset0:162 offset1:227
	s_waitcnt lgkmcnt(4)
	v_cvt_pk_bf16_f32 v156, v128, v129
	v_cvt_pk_bf16_f32 v157, v130, v131
	v_cvt_pk_bf16_f32 v158, v132, v133
	v_cvt_pk_bf16_f32 v159, v134, v135
	global_store_dwordx4 v169, v[156:159], s[54:55]
	s_add_u32 s54, s54, s49
	s_addc_u32 s55, s55, 0
	ds_read2_b32 v[144:145], v166 offset0:40 offset1:105
	ds_read2_b32 v[146:147], v166 offset0:170 offset1:235
	ds_read2_b32 v[148:149], v167 offset0:40 offset1:105
	ds_read2_b32 v[150:151], v167 offset0:170 offset1:235
	s_waitcnt lgkmcnt(4)
	v_cvt_pk_bf16_f32 v152, v136, v137
	v_cvt_pk_bf16_f32 v153, v138, v139
	v_cvt_pk_bf16_f32 v154, v140, v141
	v_cvt_pk_bf16_f32 v155, v142, v143
	global_store_dwordx4 v169, v[152:155], s[54:55]
	s_add_u32 s54, s54, s49
	s_addc_u32 s55, s55, 0
	ds_read2_b32 v[128:129], v166 offset0:48 offset1:113
	ds_read2_b32 v[130:131], v166 offset0:178 offset1:243
	ds_read2_b32 v[132:133], v167 offset0:48 offset1:113
	ds_read2_b32 v[134:135], v167 offset0:178 offset1:243
	s_waitcnt lgkmcnt(4)
	v_cvt_pk_bf16_f32 v156, v144, v145
	v_cvt_pk_bf16_f32 v157, v146, v147
	v_cvt_pk_bf16_f32 v158, v148, v149
	v_cvt_pk_bf16_f32 v159, v150, v151
	global_store_dwordx4 v169, v[156:159], s[54:55]
	s_add_u32 s54, s54, s49
	s_addc_u32 s55, s55, 0
	ds_read2_b32 v[136:137], v166 offset0:56 offset1:121
	ds_read2_b32 v[138:139], v166 offset0:186 offset1:251
	ds_read2_b32 v[140:141], v167 offset0:56 offset1:121
	ds_read2_b32 v[142:143], v167 offset0:186 offset1:251
	s_waitcnt lgkmcnt(4)
	v_cvt_pk_bf16_f32 v152, v128, v129
	v_cvt_pk_bf16_f32 v153, v130, v131
	v_cvt_pk_bf16_f32 v154, v132, v133
	v_cvt_pk_bf16_f32 v155, v134, v135
	global_store_dwordx4 v169, v[152:155], s[54:55]
	s_add_u32 s54, s54, s49
	s_addc_u32 s55, s55, 0
	s_waitcnt lgkmcnt(0)
	v_cvt_pk_bf16_f32 v156, v136, v137
	v_cvt_pk_bf16_f32 v157, v138, v139
	v_cvt_pk_bf16_f32 v158, v140, v141
	v_cvt_pk_bf16_f32 v159, v142, v143
	global_store_dwordx4 v169, v[156:159], s[54:55]
	s_cmp_lg_u32 s59, 0
	s_cbranch_scc0 cvp_done
cvp_stepB:
	s_cmp_lg_u32 s58, 0
	s_cbranch_scc0 cvp_w0B
	s_waitcnt vmcnt(32)
	s_branch cvp_goB

; #define LAS __attribute__((address_space(3)))
; #define LDS_WAIT() asm volatile("s_waitcnt lgkmcnt(0)" ::: "memory")
; __device__ __forceinline__ void tr_to_lds(const f32x4 (&v)[16], LAS float* scr, int lane) {
;     const int r4 = lane >> 4, c4 = (lane & 15) * 4;
; #pragma unroll
;     for (int i = 0; i < 16; ++i) { LAS float* s = scr + (4 * i + r4) * 65 + c4; s[0] = v[i].x; s[1] = v[i].y; s[2] = v[i].z; s[3] = v[i].w; }
;     LDS_WAIT(); asm volatile("" ::: "memory");
; }
; __device__ __forceinline__ void convert_segments(const Args& args, unsigned char* ws, LAS unsigned char* lds, int seg_lo, int seg_hi, int part_lo, int part_hi, int nparts, int wid, int nw, int wave, int lane) {
;     ...
;     for (int sI = seg_lo; sI < seg_hi; ++sI) {
;         const Seg sg = seg_at(sI);
;         const int nblk = sg.ncols / 64, nit = (sg.K / 64) * nblk;
;         const float* W = args.in[sg.in_idx] + (size_t)sg.src_l * sg.K * sg.N;
;         bf16* WT = (bf16*)(ws + WS_W + (size_t)sg.layer * LAYER_W + (size_t)sg.wsub_mib * MiB);
;         const int it_lo = (int)((long)nit * part_lo / nparts), it_hi = (int)((long)nit * part_hi / nparts);
;         int it = it_lo + wid;
;         f32x4 v[16];
;         if (it < it_hi) { const int kb = it / nblk, nb = it - kb * nblk; tr_load(W + (size_t)(64 * kb) * sg.N + sg.scol + 64 * nb, sg.N, v, lane); }
; #pragma unroll 1
;         for (; it < it_hi; it += nw) {
;             const int kb = it / nblk, nb = it - kb * nblk;
;             const int drow = sg.ilv ? (256 * (nb >> 1) + 64 * (nb & 1) + sg.drow) : (sg.drow + 64 * nb);
;             tr_to_lds(v, scr, lane);
;             const int itn = it + nw;
;             if (itn < it_hi) { const int kbn = itn / nblk, nbn = itn - kbn * nblk; tr_load(W + (size_t)(64 * kbn) * sg.N + sg.scol + 64 * nbn, sg.N, v, lane); }
cvp_goB:
	ds_write_b32 v163, v64 offset:0
	ds_write_b32 v163, v65 offset:4
	ds_write_b32 v163, v66 offset:8
	ds_write_b32 v163, v67 offset:12
	ds_write_b32 v163, v68 offset:1040
	ds_write_b32 v163, v69 offset:1044
	ds_write_b32 v163, v70 offset:1048
	ds_write_b32 v163, v71 offset:1052
	ds_write_b32 v163, v72 offset:2080
	ds_write_b32 v163, v73 offset:2084
	ds_write_b32 v163, v74 offset:2088
	ds_write_b32 v163, v75 offset:2092
	ds_write_b32 v163, v76 offset:3120
	ds_write_b32 v163, v77 offset:3124
	ds_write_b32 v163, v78 offset:3128
	ds_write_b32 v163, v79 offset:3132
	ds_write_b32 v163, v80 offset:4160
	ds_write_b32 v163, v81 offset:4164
	ds_write_b32 v163, v82 offset:4168
	ds_write_b32 v163, v83 offset:4172
	ds_write_b32 v163, v84 offset:5200
	ds_write_b32 v163, v85 offset:5204
	ds_write_b32 v163, v86 offset:5208
	ds_write_b32 v163, v87 offset:5212
	ds_write_b32 v163, v88 offset:6240
	ds_write_b32 v163, v89 offset:6244
	ds_write_b32 v163, v90 offset:6248
	ds_write_b32 v163, v91 offset:6252
	ds_write_b32 v163, v92 offset:7280
	ds_write_b32 v163, v93 offset:7284
	ds_write_b32 v163, v94 offset:7288
	ds_write_b32 v163, v95 offset:7292
	ds_write_b32 v163, v96 offset:8320
	ds_write_b32 v163, v97 offset:8324
	ds_write_b32 v163, v98 offset:8328
	ds_write_b32 v163, v99 offset:8332
	ds_write_b32 v163, v100 offset:9360
	ds_write_b32 v163, v101 offset:9364
	ds_write_b32 v163, v102 offset:9368
	ds_write_b32 v163, v103 offset:9372
	ds_write_b32 v163, v104 offset:10400
	ds_write_b32 v163, v105 offset:10404
	ds_write_b32 v163, v106 offset:10408
	ds_write_b32 v163, v107 offset:10412
	ds_write_b32 v163, v108 offset:11440
	ds_write_b32 v163, v109 offset:11444
	ds_write_b32 v163, v110 offset:11448
	ds_write_b32 v163, v111 offset:11452
	ds_write_b32 v163, v112 offset:12480
	ds_write_b32 v163, v113 offset:12484
	ds_write_b32 v163, v114 offset:12488
	ds_write_b32 v163, v115 offset:12492
	ds_write_b32 v163, v116 offset:13520
	ds_write_b32 v163, v117 offset:13524
	ds_write_b32 v163, v118 offset:13528
	ds_write_b32 v163, v119 offset:13532
	ds_write_b32 v163, v120 offset:14560
	ds_write_b32 v163, v121 offset:14564
	ds_write_b32 v163, v122 offset:14568
	ds_write_b32 v163, v123 offset:14572
	ds_write_b32 v163, v124 offset:15600
	ds_write_b32 v163, v125 offset:15604
	ds_write_b32 v163, v126 offset:15608
	ds_write_b32 v163, v127 offset:15612
	s_waitcnt lgkmcnt(0)
	s_mov_b32 s54, s78
	s_mov_b32 s55, s79
	s_lshl_b32 s49, s77, 4
	v_mul_lo_u32 v169, v165, s77
	v_lshl_add_u32 v169, v164, 3, v169
	v_lshlrev_b32_e32 v169, 1, v169
	s_mov_b32 s59, 0
cvp_nx4:
	s_cmp_lt_u32 s50, s23
	s_cbranch_scc1 cvp_nf4
	s_sub_i32 s50, s50, s23
	s_mov_b32 s23, 0
	s_add_i32 s70, s70, 1
	s_cmp_ge_i32 s70, s61
	s_cbranch_scc1 cvp_nlB
	s_mul_i32 s4, s70, 40
	s_getpc_b64 s[6:7]
	s_add_u32 s6, s6, __const._Z6seg_ati.segs@rel32@lo+4
	s_addc_u32 s7, s7, __const._Z6seg_ati.segs@rel32@hi+12
	s_add_u32 s6, s6, s4
	s_addc_u32 s7, s7, 0
	s_load_dwordx8 s[8:15], s[6:7], 0x0
	s_load_dwordx2 s[18:19], s[6:7], 0x20
	s_waitcnt lgkmcnt(0)
	s_lshr_b32 s20, s13, 6
	s_lshr_b32 s21, s11, 6
	s_mul_i32 s22, s20, s21
	s_lshl_b32 s4, s8, 3
	s_load_dwordx2 s[24:25], s[0:1], s4
	s_mul_i32 s5, s11, s10
	s_mul_i32 s5, s5, s9
	s_lshl_b32 s5, s5, 2
	s_lshl_b32 s6, s12, 2
	s_add_u32 s5, s5, s6
	s_waitcnt lgkmcnt(0)
	s_add_u32 s24, s24, s5
	s_addc_u32 s25, s25, 0
	s_mul_i32 s5, s14, 0x1a400000
	s_lshl_b32 s6, s15, 20
	s_add_u32 s5, s5, s6
	s_add_u32 s5, s5, 0x2d400000
	s_add_u32 s26, s68, s5
	s_addc_u32 s27, s69, 0
	s_mov_b32 s41, 0
	s_mov_b32 s23, s22
	v_mul_lo_u32 v168, v161, s10
	v_add_u32_e32 v168, v168, v162
	v_lshlrev_b32_e32 v168, 2, v168
	s_lshl_b32 s48, s10, 4
	s_branch cvp_nx4
cvp_nf4:
	s_add_i32 s43, s41, s50
	s_add_i32 s50, s50, s63
	v_cvt_f32_u32_e32 v170, s43
	v_cvt_f32_u32_e32 v171, s20
	v_rcp_f32_e32 v171, v171
	s_nop 1
	v_mul_f32_e32 v170, v170, v171
	v_cvt_u32_f32_e32 v170, v170
	s_nop 1
	v_readfirstlane_b32 s46, v170
	s_mul_i32 s72, s46, s20
	s_sub_i32 s47, s43, s72
	s_cmp_lt_i32 s47, 0
	s_cselect_b32 s72, s20, 0
	s_cselect_b32 s73, 1, 0
	s_add_i32 s47, s47, s72
	s_sub_i32 s46, s46, s73
	s_cmp_ge_i32 s47, s20
	s_cselect_b32 s72, s20, 0
	s_cselect_b32 s73, 1, 0
	s_sub_i32 s47, s47, s72
	s_add_i32 s46, s46, s73
	s_cmp_ge_i32 s47, s20
	s_cselect_b32 s72, s20, 0
	s_cselect_b32 s73, 1, 0
	s_sub_i32 s47, s47, s72
	s_add_i32 s46, s46, s73
	s_mul_i32 s4, s46, s10
	s_add_i32 s4, s4, s47
	s_lshl_b32 s4, s4, 8
	s_add_u32 s56, s24, s4
	s_addc_u32 s57, s25, 0
	s_lshr_b32 s4, s47, 1
	s_lshl_b32 s4, s4, 8
	s_and_b32 s5, s47, 1
	s_lshl_b32 s5, s5, 6
	s_add_i32 s4, s4, s5
	s_lshl_b32 s5, s47, 6
	s_cmp_lg_u32 s19, 0
	s_cselect_b32 s4, s4, s5
	s_add_i32 s4, s4, s18
	s_mul_i32 s4, s4, s11
	s_lshl_b32 s5, s46, 6
	s_add_i32 s4, s4, s5
	s_lshl_b32 s4, s4, 1
	s_add_u32 s78, s26, s4
	s_addc_u32 s79, s27, 0
	s_mov_b32 s77, s11
	global_load_dwordx4 v[64:67], v168, s[56:57]
	s_add_u32 s56, s56, s48
	s_addc_u32 s57, s57, 0
	global_load_dwordx4 v[68:71], v168, s[56:57]
	s_add_u32 s56, s56, s48
	s_addc_u32 s57, s57, 0
	global_load_dwordx4 v[72:75], v168, s[56:57]
	s_add_u32 s56, s56, s48
	s_addc_u32 s57, s57, 0
	global_load_dwordx4 v[76:79], v168, s[56:57]
	s_add_u32 s56, s56, s48
	s_addc_u32 s57, s57, 0
	global_load_dwordx4 v[80:83], v168, s[56:57]
	s_add_u32 s56, s56, s48
	s_addc_u32 s57, s57, 0
	global_load_dwordx4 v[84:87], v168, s[56:57]
	s_add_u32 s56, s56, s48
	s_addc_u32 s57, s57, 0
	global_load_dwordx4 v[88:91], v168, s[56:57]
	s_add_u32 s56, s56, s48
	s_addc_u32 s57, s57, 0
	global_load_dwordx4 v[92:95], v168, s[56:57]
	s_add_u32 s56, s56, s48
	s_addc_u32 s57, s57, 0
	global_load_dwordx4 v[96:99], v168, s[56:57]
	s_add_u32 s56, s56, s48
	s_addc_u32 s57, s57, 0
	global_load_dwordx4 v[100:103], v168, s[56:57]
	s_add_u32 s56, s56, s48
	s_addc_u32 s57, s57, 0
	global_load_dwordx4 v[104:107], v168, s[56:57]
	s_add_u32 s56, s56, s48
	s_addc_u32 s57, s57, 0
	global_load_dwordx4 v[108:111], v168, s[56:57]
	s_add_u32 s56, s56, s48
	s_addc_u32 s57, s57, 0
	global_load_dwordx4 v[112:115], v168, s[56:57]
	s_add_u32 s56, s56, s48
	s_addc_u32 s57, s57, 0
	global_load_dwordx4 v[116:119], v168, s[56:57]
	s_add_u32 s56, s56, s48
	s_addc_u32 s57, s57, 0
	global_load_dwordx4 v[120:123], v168, s[56:57]
	s_add_u32 s56, s56, s48
	s_addc_u32 s57, s57, 0
	global_load_dwordx4 v[124:127], v168, s[56:57]
	s_mov_b32 s59, 1
; #define LAS __attribute__((address_space(3)))
; #define LDS_WAIT() asm volatile("s_waitcnt lgkmcnt(0)" ::: "memory")
; __device__ __forceinline__ unsigned pk2(float lo, float hi) { const f32x2c v = {lo, hi}; return __builtin_bit_cast(unsigned, __builtin_convertvector(v, bf16x2c)); }
; __device__ __forceinline__ void tr_store(bf16* dst, int K, const LAS float* scr, int lane) {
;     const int c = lane & 7;
; #pragma unroll
;     for (int j = 0; j < 8; ++j) { const int n = (lane >> 3) + 8 * j; const LAS float* s = scr + (8 * c) * 65 + n;
;         v4u o; o.x = pk2(s[0], s[65]); o.y = pk2(s[130], s[195]); o.z = pk2(s[260], s[325]); o.w = pk2(s[390], s[455]);
;         *(v4u*)(dst + (size_t)n * K + 8 * c) = o; }
;     LDS_WAIT(); asm volatile("" ::: "memory");
; __device__ __forceinline__ void convert_segments(const Args& args, unsigned char* ws, LAS unsigned char* lds, int seg_lo, int seg_hi, int part_lo, int part_hi, int nparts, int wid, int nw, int wave, int lane) {
;     ...
;         for (; it < it_hi; it += nw) {
;             const int kb = it / nblk, nb = it - kb * nblk;
;             const int drow = sg.ilv ? (256 * (nb >> 1) + 64 * (nb & 1) + sg.drow) : (sg.drow + 64 * nb);
;             tr_to_lds(v, scr, lane);
;             const int itn = it + nw;
;             if (itn < it_hi) { const int kbn = itn / nblk, nbn = itn - kbn * nblk; tr_load(W + (size_t)(64 * kbn) * sg.N + sg.scol + 64 * nbn, sg.N, v, lane); }
;             tr_store(WT + (size_t)drow * sg.K + 64 * kb, sg.K, scr, lane);
;         }
cvp_nlB:
	ds_read2_b32 v[128:129], v166 offset0:0 offset1:65
	ds_read2_b32 v[130:131], v166 offset0:130 offset1:195
	ds_read2_b32 v[132:133], v167 offset0:0 offset1:65
	ds_read2_b32 v[134:135], v167 offset0:130 offset1:195
	ds_read2_b32 v[136:137], v166 offset0:8 offset1:73
	ds_read2_b32 v[138:139], v166 offset0:138 offset1:203
	ds_read2_b32 v[140:141], v167 offset0:8 offset1:73
	ds_read2_b32 v[142:143], v167 offset0:138 offset1:203
	s_waitcnt lgkmcnt(4)
	v_cvt_pk_bf16_f32 v152, v128, v129
	v_cvt_pk_bf16_f32 v153, v130, v131
	v_cvt_pk_bf16_f32 v154, v132, v133
	v_cvt_pk_bf16_f32 v155, v134, v135
	global_store_dwordx4 v169, v[152:155], s[54:55]
	s_add_u32 s54, s54, s49
	s_addc_u32 s55, s55, 0
	ds_read2_b32 v[144:145], v166 offset0:16 offset1:81
	ds_read2_b32 v[146:147], v166 offset0:146 offset1:211
	ds_read2_b32 v[148:149], v167 offset0:16 offset1:81
	ds_read2_b32 v[150:151], v167 offset0:146 offset1:211
	s_waitcnt lgkmcnt(4)
	v_cvt_pk_bf16_f32 v156, v136, v137
	v_cvt_pk_bf16_f32 v157, v138, v139
	v_cvt_pk_bf16_f32 v158, v140, v141
	v_cvt_pk_bf16_f32 v159, v142, v143
	global_store_dwordx4 v169, v[156:159], s[54:55]
	s_add_u32 s54, s54, s49
	s_addc_u32 s55, s55, 0
	ds_read2_b32 v[128:129], v166 offset0:24 offset1:89
	ds_read2_b32 v[130:131], v166 offset0:154 offset1:219
	ds_read2_b32 v[132:133], v167 offset0:24 offset1:89
	ds_read2_b32 v[134:135], v167 offset0:154 offset1:219
	s_waitcnt lgkmcnt(4)
	v_cvt_pk_bf16_f32 v152, v144, v145
	v_cvt_pk_bf16_f32 v153, v146, v147
	v_cvt_pk_bf16_f32 v154, v148, v149
	v_cvt_pk_bf16_f32 v155, v150, v151
	global_store_dwordx4 v169, v[152:155], s[54:55]
	s_add_u32 s54, s54, s49
	s_addc_u32 s55, s55, 0
	ds_read2_b32 v[136:137], v166 offset0:32 offset1:97
	ds_read2_b32 v[138:139], v166 offset0:162 offset1:227
	ds_read2_b32 v[140:141], v167 offset0:32 offset1:97
	ds_read2_b32 v[142:143], v167 offset0:162 offset1:227
	s_waitcnt lgkmcnt(4)
	v_cvt_pk_bf16_f32 v156, v128, v129
	v_cvt_pk_bf16_f32 v157, v130, v131
	v_cvt_pk_bf16_f32 v158, v132, v133
	v_cvt_pk_bf16_f32 v159, v134, v135
	global_store_dwordx4 v169, v[156:159], s[54:55]
	s_add_u32 s54, s54, s49
	s_addc_u32 s55, s55, 0
	ds_read2_b32 v[144:145], v166 offset0:40 offset1:105
	ds_read2_b32 v[146:147], v166 offset0:170 offset1:235
	ds_read2_b32 v[148:149], v167 offset0:40 offset1:105
	ds_read2_b32 v[150:151], v167 offset0:170 offset1:235
	s_waitcnt lgkmcnt(4)
	v_cvt_pk_bf16_f32 v152, v136, v137
	v_cvt_pk_bf16_f32 v153, v138, v139
	v_cvt_pk_bf16_f32 v154, v140, v141
	v_cvt_pk_bf16_f32 v155, v142, v143
	global_store_dwordx4 v169, v[152:155], s[54:55]
	s_add_u32 s54, s54, s49
	s_addc_u32 s55, s55, 0
	ds_read2_b32 v[128:129], v166 offset0:48 offset1:113
	ds_read2_b32 v[130:131], v166 offset0:178 offset1:243
	ds_read2_b32 v[132:133], v167 offset0:48 offset1:113
	ds_read2_b32 v[134:135], v167 offset0:178 offset1:243
	s_waitcnt lgkmcnt(4)
	v_cvt_pk_bf16_f32 v156, v144, v145
	v_cvt_pk_bf16_f32 v157, v146, v147
	v_cvt_pk_bf16_f32 v158, v148, v149
	v_cvt_pk_bf16_f32 v159, v150, v151
	global_store_dwordx4 v169, v[156:159], s[54:55]
	s_add_u32 s54, s54, s49
	s_addc_u32 s55, s55, 0
	ds_read2_b32 v[136:137], v166 offset0:56 offset1:121
	ds_read2_b32 v[138:139], v166 offset0:186 offset1:251
	ds_read2_b32 v[140:141], v167 offset0:56 offset1:121
	ds_read2_b32 v[142:143], v167 offset0:186 offset1:251
	s_waitcnt lgkmcnt(4)
	v_cvt_pk_bf16_f32 v152, v128, v129
	v_cvt_pk_bf16_f32 v153, v130, v131
	v_cvt_pk_bf16_f32 v154, v132, v133
	v_cvt_pk_bf16_f32 v155, v134, v135
	global_store_dwordx4 v169, v[152:155], s[54:55]
	s_add_u32 s54, s54, s49
	s_addc_u32 s55, s55, 0
	s_waitcnt lgkmcnt(0)
	v_cvt_pk_bf16_f32 v156, v136, v137
	v_cvt_pk_bf16_f32 v157, v138, v139
	v_cvt_pk_bf16_f32 v158, v140, v141
	v_cvt_pk_bf16_f32 v159, v142, v143
	global_store_dwordx4 v169, v[156:159], s[54:55]
	s_cmp_lg_u32 s58, 0
	s_cbranch_scc0 cvp_done
	s_branch cvp_stepA
